# layer-0 norm+modulation phase rewritten: all row and vector loads issued up front, eight rows reduced together
# speedup vs baseline: 1.0065x; 1.0065x over previous
; __device__ __forceinline__ void norm_mod_phase(const float* X, const float* ng, const float* mod, bf16* H, int G) {
;     int tid = threadIdx.x; asm volatile("" : "+v"(tid)); const int lane = tid & 63, wave = tid >> 6;
;     const int gw = blockIdx.x * NWAVES + wave, NGW = G * NWAVES;
; #pragma unroll 1
;     for (int b = 0; b < 2; ++b) {
;         f32x4 gs[4], sh[4];
; #pragma unroll
;         for (int j = 0; j < 4; ++j) { const int c = 4 * lane + 256 * j; gs[j] = *(const f32x4*)(ng + c) * (*(const f32x4*)(mod + b * 3072 + 1024 + c) + 1.0f); sh[j] = *(const f32x4*)(mod + b * 3072 + c); }
;         for (int tb = gw; tb < SEQL; tb += 4 * NGW) {
;             f32x4 v[4][4]; float s[4]; int mr[4]; bool has[4];
; #pragma unroll
;             for (int r = 0; r < 4; ++r) { const int t = tb + r * NGW; has[r] = t < SEQL; mr[r] = b * SEQL + (has[r] ? t : tb); const f32x4* xr = (const f32x4*)(X + (size_t)mr[r] * D) + lane;
; #pragma unroll
;                 for (int j = 0; j < 4; ++j) v[r][j] = xr[64 * j]; }
.LBB0_85:
	s_or_b64 exec, exec, s[12:13]
	s_waitcnt lgkmcnt(0)
	v_mov_b32_e32 v0, v216
	s_barrier
	s_add_u32 s12, s10, 0x1800000
	v_and_b32_e32 v1, 63, v0
	v_ashrrev_i32_e32 v0, 6, v0
	v_readlane_b32 s3, v249, 3
	v_mov_b32_e32 v3, 0
	s_addc_u32 s13, s11, 0
	v_add_u32_e32 v110, s3, v0
	v_lshlrev_b32_e32 v0, 2, v1
	v_lshlrev_b32_e32 v2, 4, v1
	v_lshlrev_b32_e32 v4, 3, v1
	v_mov_b32_e32 v5, v3
	v_lshl_add_u64 v[80:81], s[68:69], 0, v[2:3]
	v_lshl_add_u64 v[82:83], s[12:13], 0, v[4:5]
	v_lshl_add_u64 v[84:85], s[72:73], 0, v[2:3]
	v_or_b32_e32 v2, 0x100, v0
	v_or_b32_e32 v4, 0x200, v0
	v_or_b32_e32 v6, 0x300, v0
	v_lshlrev_b32_e32 v111, 2, v0
	v_mbcnt_lo_u32_b32 v0, -1, 0
	v_mbcnt_hi_u32_b32 v208, -1, v0
	s_movk_i32 s3, 0x2000
	s_add_i32 s7, s4, s4
	v_and_b32_e32 v217, 64, v208
	v_cmp_gt_i32_e64 s[36:37], s3, v110
	s_lshl_b32 s5, s6, 4
	s_mov_b32 s21, 0
	s_mov_b64 s[22:23], -1
	v_lshlrev_b32_e32 v112, 2, v2
	v_lshlrev_b32_e32 v113, 2, v4
	v_lshlrev_b32_e32 v114, 2, v6
	v_mov_b32_e32 v115, 0x358637bd
	s_add_i32 s7, s7, s4
	v_add_u32_e32 v209, 64, v217
	v_xor_b32_e32 v215, 1, v208
	v_xor_b32_e32 v214, 2, v208
	v_xor_b32_e32 v213, 4, v208
	v_xor_b32_e32 v212, 8, v208
	v_xor_b32_e32 v211, 16, v208
	v_xor_b32_e32 v210, 32, v208
	s_cmp_eq_u32 s6, 0x100
	s_cbranch_scc0 .Lnorm_orig
	v_lshlrev_b32_e32 v107, 4, v208
	v_lshlrev_b32_e32 v106, 3, v208
	v_readfirstlane_b32 s16, v110
	s_lshl_b32 s14, s6, 3
	s_add_u32 s38, s0, 0x1000
	s_addc_u32 s39, s1, 0
	s_add_u32 s40, s0, 0x3000
	s_addc_u32 s41, s1, 0
	s_add_u32 s42, s0, 0x4000
	s_addc_u32 s43, s1, 0
	global_load_dwordx4 v[0:3], v107, s[72:73]
	global_load_dwordx4 v[4:7], v107, s[72:73] offset:1024
	global_load_dwordx4 v[8:11], v107, s[72:73] offset:2048
	global_load_dwordx4 v[12:15], v107, s[72:73] offset:3072
	global_load_dwordx4 v[16:19], v107, s[38:39]
	global_load_dwordx4 v[20:23], v107, s[38:39] offset:1024
	global_load_dwordx4 v[24:27], v107, s[38:39] offset:2048
	global_load_dwordx4 v[28:31], v107, s[38:39] offset:3072
	global_load_dwordx4 v[32:35], v107, s[0:1]
	global_load_dwordx4 v[36:39], v107, s[0:1] offset:1024
	global_load_dwordx4 v[40:43], v107, s[0:1] offset:2048
	global_load_dwordx4 v[44:47], v107, s[0:1] offset:3072
	global_load_dwordx4 v[48:51], v107, s[42:43]
	global_load_dwordx4 v[52:55], v107, s[42:43] offset:1024
	global_load_dwordx4 v[56:59], v107, s[42:43] offset:2048
	global_load_dwordx4 v[60:63], v107, s[42:43] offset:3072
	global_load_dwordx4 v[64:67], v107, s[40:41]
	global_load_dwordx4 v[68:71], v107, s[40:41] offset:1024
	global_load_dwordx4 v[72:75], v107, s[40:41] offset:2048
	global_load_dwordx4 v[76:79], v107, s[40:41] offset:3072
	s_mov_b32 s18, s16
	s_lshl_b32 s20, s18, 12
	s_add_u32 s22, s68, s20
	s_addc_u32 s23, s69, 0
	global_load_dwordx4 v[116:119], v107, s[22:23]
	global_load_dwordx4 v[120:123], v107, s[22:23] offset:1024
	global_load_dwordx4 v[124:127], v107, s[22:23] offset:2048
	global_load_dwordx4 v[128:131], v107, s[22:23] offset:3072
	s_add_i32 s18, s18, s14
	s_lshl_b32 s20, s18, 12
	s_add_u32 s22, s68, s20
	s_addc_u32 s23, s69, 0
	global_load_dwordx4 v[132:135], v107, s[22:23]
	global_load_dwordx4 v[136:139], v107, s[22:23] offset:1024
	global_load_dwordx4 v[140:143], v107, s[22:23] offset:2048
	global_load_dwordx4 v[144:147], v107, s[22:23] offset:3072
	s_add_i32 s18, s18, s14
	s_lshl_b32 s20, s18, 12
	s_add_u32 s22, s68, s20
	s_addc_u32 s23, s69, 0
	global_load_dwordx4 v[148:151], v107, s[22:23]
	global_load_dwordx4 v[152:155], v107, s[22:23] offset:1024
	global_load_dwordx4 v[156:159], v107, s[22:23] offset:2048
	global_load_dwordx4 v[160:163], v107, s[22:23] offset:3072
	s_add_i32 s18, s18, s14
	s_lshl_b32 s20, s18, 12
	s_add_u32 s22, s68, s20
	s_addc_u32 s23, s69, 0
	global_load_dwordx4 v[164:167], v107, s[22:23]
	global_load_dwordx4 v[168:171], v107, s[22:23] offset:1024
	global_load_dwordx4 v[172:175], v107, s[22:23] offset:2048
	global_load_dwordx4 v[176:179], v107, s[22:23] offset:3072
	s_add_i32 s18, s16, 8192
	s_lshl_b32 s20, s18, 12
	s_add_u32 s22, s68, s20
	s_addc_u32 s23, s69, 0
	global_load_dwordx4 v[180:183], v107, s[22:23]
	global_load_dwordx4 v[184:187], v107, s[22:23] offset:1024
	global_load_dwordx4 v[188:191], v107, s[22:23] offset:2048
	global_load_dwordx4 v[192:195], v107, s[22:23] offset:3072
	s_add_i32 s18, s18, s14
	s_lshl_b32 s20, s18, 12
	s_add_u32 s22, s68, s20
	s_addc_u32 s23, s69, 0
	global_load_dwordx4 v[86:89], v107, s[22:23]
	global_load_dwordx4 v[90:93], v107, s[22:23] offset:1024
	global_load_dwordx4 v[94:97], v107, s[22:23] offset:2048
	global_load_dwordx4 v[98:101], v107, s[22:23] offset:3072
	s_add_i32 s18, s18, s14
	s_lshl_b32 s20, s18, 12
	s_add_u32 s22, s68, s20
	s_addc_u32 s23, s69, 0
	global_load_dwordx4 v[218:221], v107, s[22:23]
	global_load_dwordx4 v[222:225], v107, s[22:23] offset:1024
	global_load_dwordx4 v[226:229], v107, s[22:23] offset:2048
	global_load_dwordx4 v[230:233], v107, s[22:23] offset:3072
	s_add_i32 s18, s18, s14
	s_lshl_b32 s20, s18, 12
	s_add_u32 s22, s68, s20
	s_addc_u32 s23, s69, 0
	global_load_dwordx4 v[196:199], v107, s[22:23]
	global_load_dwordx4 v[200:203], v107, s[22:23] offset:1024
	global_load_dwordx4 v[204:207], v107, s[22:23] offset:2048
	global_load_dwordx4 v[102:105], v107, s[22:23] offset:3072
	v_xor_b32_e32 v242, 1, v208
	v_lshlrev_b32_e32 v242, 2, v242
	v_xor_b32_e32 v243, 2, v208
	v_lshlrev_b32_e32 v243, 2, v243
	v_xor_b32_e32 v244, 4, v208
	v_lshlrev_b32_e32 v244, 2, v244
	v_xor_b32_e32 v245, 8, v208
	v_lshlrev_b32_e32 v245, 2, v245
	v_xor_b32_e32 v246, 16, v208
	v_lshlrev_b32_e32 v246, 2, v246
	v_xor_b32_e32 v247, 32, v208
	v_lshlrev_b32_e32 v247, 2, v247
	v_mov_b32_e32 v108, 0x358637bd
	s_waitcnt vmcnt(32)
; __device__ __forceinline__ void norm_mod_phase(const float* X, const float* ng, const float* mod, bf16* H, int G) {
;     ...
;         for (int j = 0; j < 4; ++j) { const int c = 4 * lane + 256 * j; gs[j] = *(const f32x4*)(ng + c) * (*(const f32x4*)(mod + b * 3072 + 1024 + c) + 1.0f); sh[j] = *(const f32x4*)(mod + b * 3072 + c); }
;         for (int tb = gw; tb < SEQL; tb += 4 * NGW) {
;             f32x4 v[4][4]; float s[4]; int mr[4]; bool has[4];
; #pragma unroll
;             for (int r = 0; r < 4; ++r) { const int t = tb + r * NGW; has[r] = t < SEQL; mr[r] = b * SEQL + (has[r] ? t : tb); const f32x4* xr = (const f32x4*)(X + (size_t)mr[r] * D) + lane;
; #pragma unroll
;                 for (int j = 0; j < 4; ++j) v[r][j] = xr[64 * j]; }
; #pragma unroll
;             for (int r = 0; r < 4; ++r) { float q = 0.f;
; #pragma unroll
;                 for (int j = 0; j < 4; ++j) q += (v[r][j].x * v[r][j].x + v[r][j].y * v[r][j].y) + (v[r][j].z * v[r][j].z + v[r][j].w * v[r][j].w);
;                 s[r] = q; }
	v_add_f32_e32 v16, 1.0, v16
	v_add_f32_e32 v17, 1.0, v17
	v_add_f32_e32 v18, 1.0, v18
	v_add_f32_e32 v19, 1.0, v19
	v_add_f32_e32 v20, 1.0, v20
	v_add_f32_e32 v21, 1.0, v21
	v_add_f32_e32 v22, 1.0, v22
	v_add_f32_e32 v23, 1.0, v23
	v_add_f32_e32 v24, 1.0, v24
	v_add_f32_e32 v25, 1.0, v25
	v_add_f32_e32 v26, 1.0, v26
	v_add_f32_e32 v27, 1.0, v27
	v_add_f32_e32 v28, 1.0, v28
	v_add_f32_e32 v29, 1.0, v29
	v_add_f32_e32 v30, 1.0, v30
	v_add_f32_e32 v31, 1.0, v31
	v_mul_f32_e32 v16, v0, v16
	v_mul_f32_e32 v17, v1, v17
	v_mul_f32_e32 v18, v2, v18
	v_mul_f32_e32 v19, v3, v19
	v_mul_f32_e32 v20, v4, v20
	v_mul_f32_e32 v21, v5, v21
	v_mul_f32_e32 v22, v6, v22
	v_mul_f32_e32 v23, v7, v23
	v_mul_f32_e32 v24, v8, v24
	v_mul_f32_e32 v25, v9, v25
	v_mul_f32_e32 v26, v10, v26
	v_mul_f32_e32 v27, v11, v27
	v_mul_f32_e32 v28, v12, v28
	v_mul_f32_e32 v29, v13, v29
	v_mul_f32_e32 v30, v14, v30
	v_mul_f32_e32 v31, v15, v31
	v_add_f32_e32 v48, 1.0, v48
	v_add_f32_e32 v49, 1.0, v49
	v_add_f32_e32 v50, 1.0, v50
	v_add_f32_e32 v51, 1.0, v51
	v_add_f32_e32 v52, 1.0, v52
	v_add_f32_e32 v53, 1.0, v53
	v_add_f32_e32 v54, 1.0, v54
	v_add_f32_e32 v55, 1.0, v55
	v_add_f32_e32 v56, 1.0, v56
	v_add_f32_e32 v57, 1.0, v57
	v_add_f32_e32 v58, 1.0, v58
	v_add_f32_e32 v59, 1.0, v59
	v_add_f32_e32 v60, 1.0, v60
	v_add_f32_e32 v61, 1.0, v61
	v_add_f32_e32 v62, 1.0, v62
	v_add_f32_e32 v63, 1.0, v63
	v_mul_f32_e32 v48, v0, v48
	v_mul_f32_e32 v49, v1, v49
	v_mul_f32_e32 v50, v2, v50
	v_mul_f32_e32 v51, v3, v51
	v_mul_f32_e32 v52, v4, v52
	v_mul_f32_e32 v53, v5, v53
	v_mul_f32_e32 v54, v6, v54
	v_mul_f32_e32 v55, v7, v55
	v_mul_f32_e32 v56, v8, v56
	v_mul_f32_e32 v57, v9, v57
	v_mul_f32_e32 v58, v10, v58
	v_mul_f32_e32 v59, v11, v59
	v_mul_f32_e32 v60, v12, v60
	v_mul_f32_e32 v61, v13, v61
	v_mul_f32_e32 v62, v14, v62
	v_mul_f32_e32 v63, v15, v63
	s_waitcnt vmcnt(28)
	v_mul_f32_e32 v250, v116, v116
	v_mul_f32_e32 v251, v118, v118
	v_fmac_f32_e32 v250, v117, v117
	v_fmac_f32_e32 v251, v119, v119
	v_add_f32_e32 v234, v250, v251
	v_mul_f32_e32 v250, v120, v120
	v_mul_f32_e32 v251, v122, v122
	v_fmac_f32_e32 v250, v121, v121
	v_fmac_f32_e32 v251, v123, v123
	v_add_f32_e32 v250, v250, v251
	v_add_f32_e32 v234, v234, v250
	v_mul_f32_e32 v250, v124, v124
	v_mul_f32_e32 v251, v126, v126
	v_fmac_f32_e32 v250, v125, v125
	v_fmac_f32_e32 v251, v127, v127
	v_add_f32_e32 v250, v250, v251
	v_add_f32_e32 v234, v234, v250
	v_mul_f32_e32 v250, v128, v128
	v_mul_f32_e32 v251, v130, v130
	v_fmac_f32_e32 v250, v129, v129
	v_fmac_f32_e32 v251, v131, v131
	v_add_f32_e32 v250, v250, v251
	v_add_f32_e32 v234, v234, v250
	s_waitcnt vmcnt(24)
	v_mul_f32_e32 v250, v132, v132
	v_mul_f32_e32 v251, v134, v134
	v_fmac_f32_e32 v250, v133, v133
	v_fmac_f32_e32 v251, v135, v135
	v_add_f32_e32 v235, v250, v251
	v_mul_f32_e32 v250, v136, v136
	v_mul_f32_e32 v251, v138, v138
	v_fmac_f32_e32 v250, v137, v137
	v_fmac_f32_e32 v251, v139, v139
	v_add_f32_e32 v250, v250, v251
	v_add_f32_e32 v235, v235, v250
	v_mul_f32_e32 v250, v140, v140
	v_mul_f32_e32 v251, v142, v142
	v_fmac_f32_e32 v250, v141, v141
	v_fmac_f32_e32 v251, v143, v143
	v_add_f32_e32 v250, v250, v251
	v_add_f32_e32 v235, v235, v250
	v_mul_f32_e32 v250, v144, v144
	v_mul_f32_e32 v251, v146, v146
	v_fmac_f32_e32 v250, v145, v145
	v_fmac_f32_e32 v251, v147, v147
	v_add_f32_e32 v250, v250, v251
	v_add_f32_e32 v235, v235, v250
	s_waitcnt vmcnt(20)
	v_mul_f32_e32 v250, v148, v148
	v_mul_f32_e32 v251, v150, v150
	v_fmac_f32_e32 v250, v149, v149
	v_fmac_f32_e32 v251, v151, v151
	v_add_f32_e32 v236, v250, v251
	v_mul_f32_e32 v250, v152, v152
	v_mul_f32_e32 v251, v154, v154
	v_fmac_f32_e32 v250, v153, v153
	v_fmac_f32_e32 v251, v155, v155
	v_add_f32_e32 v250, v250, v251
	v_add_f32_e32 v236, v236, v250
	v_mul_f32_e32 v250, v156, v156
	v_mul_f32_e32 v251, v158, v158
	v_fmac_f32_e32 v250, v157, v157
	v_fmac_f32_e32 v251, v159, v159
	v_add_f32_e32 v250, v250, v251
	v_add_f32_e32 v236, v236, v250
	v_mul_f32_e32 v250, v160, v160
	v_mul_f32_e32 v251, v162, v162
	v_fmac_f32_e32 v250, v161, v161
	v_fmac_f32_e32 v251, v163, v163
	v_add_f32_e32 v250, v250, v251
	v_add_f32_e32 v236, v236, v250
	s_waitcnt vmcnt(16)
	v_mul_f32_e32 v250, v164, v164
	v_mul_f32_e32 v251, v166, v166
	v_fmac_f32_e32 v250, v165, v165
	v_fmac_f32_e32 v251, v167, v167
	v_add_f32_e32 v237, v250, v251
	v_mul_f32_e32 v250, v168, v168
	v_mul_f32_e32 v251, v170, v170
	v_fmac_f32_e32 v250, v169, v169
	v_fmac_f32_e32 v251, v171, v171
	v_add_f32_e32 v250, v250, v251
	v_add_f32_e32 v237, v237, v250
	v_mul_f32_e32 v250, v172, v172
	v_mul_f32_e32 v251, v174, v174
	v_fmac_f32_e32 v250, v173, v173
	v_fmac_f32_e32 v251, v175, v175
	v_add_f32_e32 v250, v250, v251
	v_add_f32_e32 v237, v237, v250
	v_mul_f32_e32 v250, v176, v176
	v_mul_f32_e32 v251, v178, v178
	v_fmac_f32_e32 v250, v177, v177
	v_fmac_f32_e32 v251, v179, v179
	v_add_f32_e32 v250, v250, v251
	v_add_f32_e32 v237, v237, v250
	s_waitcnt vmcnt(12)
	v_mul_f32_e32 v250, v180, v180
	v_mul_f32_e32 v251, v182, v182
	v_fmac_f32_e32 v250, v181, v181
	v_fmac_f32_e32 v251, v183, v183
	v_add_f32_e32 v238, v250, v251
	v_mul_f32_e32 v250, v184, v184
	v_mul_f32_e32 v251, v186, v186
	v_fmac_f32_e32 v250, v185, v185
	v_fmac_f32_e32 v251, v187, v187
	v_add_f32_e32 v250, v250, v251
	v_add_f32_e32 v238, v238, v250
	v_mul_f32_e32 v250, v188, v188
	v_mul_f32_e32 v251, v190, v190
	v_fmac_f32_e32 v250, v189, v189
	v_fmac_f32_e32 v251, v191, v191
	v_add_f32_e32 v250, v250, v251
	v_add_f32_e32 v238, v238, v250
	v_mul_f32_e32 v250, v192, v192
	v_mul_f32_e32 v251, v194, v194
	v_fmac_f32_e32 v250, v193, v193
	v_fmac_f32_e32 v251, v195, v195
	v_add_f32_e32 v250, v250, v251
	v_add_f32_e32 v238, v238, v250
	s_waitcnt vmcnt(8)
; __device__ __forceinline__ void norm_mod_phase(const float* X, const float* ng, const float* mod, bf16* H, int G) {
;     ...
;             for (int r = 0; r < 4; ++r) { float q = 0.f;
; #pragma unroll
;                 for (int j = 0; j < 4; ++j) q += (v[r][j].x * v[r][j].x + v[r][j].y * v[r][j].y) + (v[r][j].z * v[r][j].z + v[r][j].w * v[r][j].w);
;                 s[r] = q; }
; #pragma unroll
;             for (int o = 1; o < 64; o <<= 1) {
; #pragma unroll
;                 for (int r = 0; r < 4; ++r) s[r] += __shfl_xor(s[r], o); }
	v_mul_f32_e32 v250, v86, v86
	v_mul_f32_e32 v251, v88, v88
	v_fmac_f32_e32 v250, v87, v87
	v_fmac_f32_e32 v251, v89, v89
	v_add_f32_e32 v239, v250, v251
	v_mul_f32_e32 v250, v90, v90
	v_mul_f32_e32 v251, v92, v92
	v_fmac_f32_e32 v250, v91, v91
	v_fmac_f32_e32 v251, v93, v93
	v_add_f32_e32 v250, v250, v251
	v_add_f32_e32 v239, v239, v250
	v_mul_f32_e32 v250, v94, v94
	v_mul_f32_e32 v251, v96, v96
	v_fmac_f32_e32 v250, v95, v95
	v_fmac_f32_e32 v251, v97, v97
	v_add_f32_e32 v250, v250, v251
	v_add_f32_e32 v239, v239, v250
	v_mul_f32_e32 v250, v98, v98
	v_mul_f32_e32 v251, v100, v100
	v_fmac_f32_e32 v250, v99, v99
	v_fmac_f32_e32 v251, v101, v101
	v_add_f32_e32 v250, v250, v251
	v_add_f32_e32 v239, v239, v250
	s_waitcnt vmcnt(4)
	v_mul_f32_e32 v250, v218, v218
	v_mul_f32_e32 v251, v220, v220
	v_fmac_f32_e32 v250, v219, v219
	v_fmac_f32_e32 v251, v221, v221
	v_add_f32_e32 v240, v250, v251
	v_mul_f32_e32 v250, v222, v222
	v_mul_f32_e32 v251, v224, v224
	v_fmac_f32_e32 v250, v223, v223
	v_fmac_f32_e32 v251, v225, v225
	v_add_f32_e32 v250, v250, v251
	v_add_f32_e32 v240, v240, v250
	v_mul_f32_e32 v250, v226, v226
	v_mul_f32_e32 v251, v228, v228
	v_fmac_f32_e32 v250, v227, v227
	v_fmac_f32_e32 v251, v229, v229
	v_add_f32_e32 v250, v250, v251
	v_add_f32_e32 v240, v240, v250
	v_mul_f32_e32 v250, v230, v230
	v_mul_f32_e32 v251, v232, v232
	v_fmac_f32_e32 v250, v231, v231
	v_fmac_f32_e32 v251, v233, v233
	v_add_f32_e32 v250, v250, v251
	v_add_f32_e32 v240, v240, v250
	s_waitcnt vmcnt(0)
	v_mul_f32_e32 v250, v196, v196
	v_mul_f32_e32 v251, v198, v198
	v_fmac_f32_e32 v250, v197, v197
	v_fmac_f32_e32 v251, v199, v199
	v_add_f32_e32 v241, v250, v251
	v_mul_f32_e32 v250, v200, v200
	v_mul_f32_e32 v251, v202, v202
	v_fmac_f32_e32 v250, v201, v201
	v_fmac_f32_e32 v251, v203, v203
	v_add_f32_e32 v250, v250, v251
	v_add_f32_e32 v241, v241, v250
	v_mul_f32_e32 v250, v204, v204
	v_mul_f32_e32 v251, v206, v206
	v_fmac_f32_e32 v250, v205, v205
	v_fmac_f32_e32 v251, v207, v207
	v_add_f32_e32 v250, v250, v251
	v_add_f32_e32 v241, v241, v250
	v_mul_f32_e32 v250, v102, v102
	v_mul_f32_e32 v251, v104, v104
	v_fmac_f32_e32 v250, v103, v103
	v_fmac_f32_e32 v251, v105, v105
	v_add_f32_e32 v250, v250, v251
	v_add_f32_e32 v241, v241, v250
	ds_bpermute_b32 v109, v242, v234
	ds_bpermute_b32 v110, v242, v235
	ds_bpermute_b32 v111, v242, v236
	ds_bpermute_b32 v112, v242, v237
	ds_bpermute_b32 v113, v242, v238
	ds_bpermute_b32 v114, v242, v239
	ds_bpermute_b32 v252, v242, v240
	ds_bpermute_b32 v253, v242, v241
	s_waitcnt lgkmcnt(7)
	v_add_f32_e32 v234, v234, v109
	s_waitcnt lgkmcnt(6)
	v_add_f32_e32 v235, v235, v110
	s_waitcnt lgkmcnt(5)
	v_add_f32_e32 v236, v236, v111
	s_waitcnt lgkmcnt(4)
	v_add_f32_e32 v237, v237, v112
	s_waitcnt lgkmcnt(3)
	v_add_f32_e32 v238, v238, v113
	s_waitcnt lgkmcnt(2)
	v_add_f32_e32 v239, v239, v114
	s_waitcnt lgkmcnt(1)
	v_add_f32_e32 v240, v240, v252
	s_waitcnt lgkmcnt(0)
	v_add_f32_e32 v241, v241, v253
	ds_bpermute_b32 v109, v243, v234
	ds_bpermute_b32 v110, v243, v235
	ds_bpermute_b32 v111, v243, v236
	ds_bpermute_b32 v112, v243, v237
	ds_bpermute_b32 v113, v243, v238
	ds_bpermute_b32 v114, v243, v239
	ds_bpermute_b32 v252, v243, v240
	ds_bpermute_b32 v253, v243, v241
	s_waitcnt lgkmcnt(7)
	v_add_f32_e32 v234, v234, v109
	s_waitcnt lgkmcnt(6)
	v_add_f32_e32 v235, v235, v110
	s_waitcnt lgkmcnt(5)
	v_add_f32_e32 v236, v236, v111
	s_waitcnt lgkmcnt(4)
	v_add_f32_e32 v237, v237, v112
	s_waitcnt lgkmcnt(3)
	v_add_f32_e32 v238, v238, v113
	s_waitcnt lgkmcnt(2)
	v_add_f32_e32 v239, v239, v114
	s_waitcnt lgkmcnt(1)
	v_add_f32_e32 v240, v240, v252
	s_waitcnt lgkmcnt(0)
	v_add_f32_e32 v241, v241, v253
	ds_bpermute_b32 v109, v244, v234
	ds_bpermute_b32 v110, v244, v235
	ds_bpermute_b32 v111, v244, v236
	ds_bpermute_b32 v112, v244, v237
	ds_bpermute_b32 v113, v244, v238
	ds_bpermute_b32 v114, v244, v239
	ds_bpermute_b32 v252, v244, v240
	ds_bpermute_b32 v253, v244, v241
	s_waitcnt lgkmcnt(7)
	v_add_f32_e32 v234, v234, v109
	s_waitcnt lgkmcnt(6)
	v_add_f32_e32 v235, v235, v110
	s_waitcnt lgkmcnt(5)
	v_add_f32_e32 v236, v236, v111
	s_waitcnt lgkmcnt(4)
	v_add_f32_e32 v237, v237, v112
	s_waitcnt lgkmcnt(3)
	v_add_f32_e32 v238, v238, v113
	s_waitcnt lgkmcnt(2)
	v_add_f32_e32 v239, v239, v114
	s_waitcnt lgkmcnt(1)
	v_add_f32_e32 v240, v240, v252
	s_waitcnt lgkmcnt(0)
	v_add_f32_e32 v241, v241, v253
	ds_bpermute_b32 v109, v245, v234
	ds_bpermute_b32 v110, v245, v235
	ds_bpermute_b32 v111, v245, v236
	ds_bpermute_b32 v112, v245, v237
	ds_bpermute_b32 v113, v245, v238
	ds_bpermute_b32 v114, v245, v239
	ds_bpermute_b32 v252, v245, v240
	ds_bpermute_b32 v253, v245, v241
	s_waitcnt lgkmcnt(7)
	v_add_f32_e32 v234, v234, v109
	s_waitcnt lgkmcnt(6)
	v_add_f32_e32 v235, v235, v110
	s_waitcnt lgkmcnt(5)
	v_add_f32_e32 v236, v236, v111
	s_waitcnt lgkmcnt(4)
	v_add_f32_e32 v237, v237, v112
	s_waitcnt lgkmcnt(3)
	v_add_f32_e32 v238, v238, v113
	s_waitcnt lgkmcnt(2)
	v_add_f32_e32 v239, v239, v114
	s_waitcnt lgkmcnt(1)
	v_add_f32_e32 v240, v240, v252
	s_waitcnt lgkmcnt(0)
	v_add_f32_e32 v241, v241, v253
	ds_bpermute_b32 v109, v246, v234
	ds_bpermute_b32 v110, v246, v235
	ds_bpermute_b32 v111, v246, v236
	ds_bpermute_b32 v112, v246, v237
	ds_bpermute_b32 v113, v246, v238
	ds_bpermute_b32 v114, v246, v239
	ds_bpermute_b32 v252, v246, v240
	ds_bpermute_b32 v253, v246, v241
	s_waitcnt lgkmcnt(7)
	v_add_f32_e32 v234, v234, v109
	s_waitcnt lgkmcnt(6)
	v_add_f32_e32 v235, v235, v110
	s_waitcnt lgkmcnt(5)
	v_add_f32_e32 v236, v236, v111
	s_waitcnt lgkmcnt(4)
	v_add_f32_e32 v237, v237, v112
	s_waitcnt lgkmcnt(3)
	v_add_f32_e32 v238, v238, v113
	s_waitcnt lgkmcnt(2)
; __device__ __forceinline__ unsigned pk2(float lo, float hi) { f32x2_t v = {lo, hi}; bf16x2_t b = __builtin_convertvector(v, bf16x2_t); return __builtin_bit_cast(unsigned, b); }
; __device__ __forceinline__ void norm_mod_phase(const float* X, const float* ng, const float* mod, bf16* H, int G) {
;     ...
;             for (int o = 1; o < 64; o <<= 1) {
; #pragma unroll
;                 for (int r = 0; r < 4; ++r) s[r] += __shfl_xor(s[r], o); }
; #pragma unroll
;             for (int r = 0; r < 4; ++r) { if (!has[r]) continue;
;                 const float rs = __builtin_amdgcn_rsqf(s[r] * (1.f / D) + EPSN); v2u* o8 = (v2u*)(H + (size_t)mr[r] * D) + lane;
; #pragma unroll
;                 for (int j = 0; j < 4; ++j) { const f32x4 h = v[r][j] * rs * gs[j] + sh[j]; o8[64 * j] = (v2u){pk2(h.x, h.y), pk2(h.z, h.w)}; } }
	v_add_f32_e32 v239, v239, v114
	s_waitcnt lgkmcnt(1)
	v_add_f32_e32 v240, v240, v252
	s_waitcnt lgkmcnt(0)
	v_add_f32_e32 v241, v241, v253
	ds_bpermute_b32 v109, v247, v234
	ds_bpermute_b32 v110, v247, v235
	ds_bpermute_b32 v111, v247, v236
	ds_bpermute_b32 v112, v247, v237
	ds_bpermute_b32 v113, v247, v238
	ds_bpermute_b32 v114, v247, v239
	ds_bpermute_b32 v252, v247, v240
	ds_bpermute_b32 v253, v247, v241
	s_waitcnt lgkmcnt(7)
	v_add_f32_e32 v234, v234, v109
	s_waitcnt lgkmcnt(6)
	v_add_f32_e32 v235, v235, v110
	s_waitcnt lgkmcnt(5)
	v_add_f32_e32 v236, v236, v111
	s_waitcnt lgkmcnt(4)
	v_add_f32_e32 v237, v237, v112
	s_waitcnt lgkmcnt(3)
	v_add_f32_e32 v238, v238, v113
	s_waitcnt lgkmcnt(2)
	v_add_f32_e32 v239, v239, v114
	s_waitcnt lgkmcnt(1)
	v_add_f32_e32 v240, v240, v252
	s_waitcnt lgkmcnt(0)
	v_add_f32_e32 v241, v241, v253
	v_fmamk_f32 v234, v234, 0x3a800000, v108
	v_fmamk_f32 v235, v235, 0x3a800000, v108
	v_fmamk_f32 v236, v236, 0x3a800000, v108
	v_fmamk_f32 v237, v237, 0x3a800000, v108
	v_fmamk_f32 v238, v238, 0x3a800000, v108
	v_fmamk_f32 v239, v239, 0x3a800000, v108
	v_fmamk_f32 v240, v240, 0x3a800000, v108
	v_fmamk_f32 v241, v241, 0x3a800000, v108
	v_rsq_f32_e32 v234, v234
	v_rsq_f32_e32 v235, v235
	v_rsq_f32_e32 v236, v236
	v_rsq_f32_e32 v237, v237
	v_rsq_f32_e32 v238, v238
	v_rsq_f32_e32 v239, v239
	v_rsq_f32_e32 v240, v240
	v_rsq_f32_e32 v241, v241
	s_nop 0
	s_mov_b32 s18, s16
	s_lshl_b32 s20, s18, 11
	s_add_u32 s22, s12, s20
	s_addc_u32 s23, s13, 0
	v_mul_f32_e32 v116, v116, v234
	v_mul_f32_e32 v117, v117, v234
	v_mul_f32_e32 v118, v118, v234
	v_mul_f32_e32 v119, v119, v234
	v_fma_f32 v116, v116, v16, v32
	v_fma_f32 v117, v117, v17, v33
	v_fma_f32 v118, v118, v18, v34
	v_fma_f32 v119, v119, v19, v35
	v_cvt_pk_bf16_f32 v116, v116, v117
	v_cvt_pk_bf16_f32 v117, v118, v119
	global_store_dwordx2 v106, v[116:117], s[22:23]
	v_mul_f32_e32 v120, v120, v234
	v_mul_f32_e32 v121, v121, v234
	v_mul_f32_e32 v122, v122, v234
	v_mul_f32_e32 v123, v123, v234
	v_fma_f32 v120, v120, v20, v36
	v_fma_f32 v121, v121, v21, v37
	v_fma_f32 v122, v122, v22, v38
	v_fma_f32 v123, v123, v23, v39
	v_cvt_pk_bf16_f32 v120, v120, v121
	v_cvt_pk_bf16_f32 v121, v122, v123
	global_store_dwordx2 v106, v[120:121], s[22:23] offset:512
	v_mul_f32_e32 v124, v124, v234
	v_mul_f32_e32 v125, v125, v234
	v_mul_f32_e32 v126, v126, v234
	v_mul_f32_e32 v127, v127, v234
	v_fma_f32 v124, v124, v24, v40
	v_fma_f32 v125, v125, v25, v41
	v_fma_f32 v126, v126, v26, v42
	v_fma_f32 v127, v127, v27, v43
	v_cvt_pk_bf16_f32 v124, v124, v125
	v_cvt_pk_bf16_f32 v125, v126, v127
	global_store_dwordx2 v106, v[124:125], s[22:23] offset:1024
	v_mul_f32_e32 v128, v128, v234
	v_mul_f32_e32 v129, v129, v234
	v_mul_f32_e32 v130, v130, v234
	v_mul_f32_e32 v131, v131, v234
	v_fma_f32 v128, v128, v28, v44
	v_fma_f32 v129, v129, v29, v45
	v_fma_f32 v130, v130, v30, v46
	v_fma_f32 v131, v131, v31, v47
	v_cvt_pk_bf16_f32 v128, v128, v129
	v_cvt_pk_bf16_f32 v129, v130, v131
	global_store_dwordx2 v106, v[128:129], s[22:23] offset:1536
	s_add_i32 s18, s18, s14
	s_lshl_b32 s20, s18, 11
	s_add_u32 s22, s12, s20
	s_addc_u32 s23, s13, 0
	v_mul_f32_e32 v132, v132, v235
	v_mul_f32_e32 v133, v133, v235
	v_mul_f32_e32 v134, v134, v235
	v_mul_f32_e32 v135, v135, v235
	v_fma_f32 v132, v132, v16, v32
	v_fma_f32 v133, v133, v17, v33
	v_fma_f32 v134, v134, v18, v34
	v_fma_f32 v135, v135, v19, v35
	v_cvt_pk_bf16_f32 v132, v132, v133
	v_cvt_pk_bf16_f32 v133, v134, v135
	global_store_dwordx2 v106, v[132:133], s[22:23]
	v_mul_f32_e32 v136, v136, v235
	v_mul_f32_e32 v137, v137, v235
	v_mul_f32_e32 v138, v138, v235
	v_mul_f32_e32 v139, v139, v235
	v_fma_f32 v136, v136, v20, v36
	v_fma_f32 v137, v137, v21, v37
	v_fma_f32 v138, v138, v22, v38
	v_fma_f32 v139, v139, v23, v39
	v_cvt_pk_bf16_f32 v136, v136, v137
	v_cvt_pk_bf16_f32 v137, v138, v139
	global_store_dwordx2 v106, v[136:137], s[22:23] offset:512
	v_mul_f32_e32 v140, v140, v235
	v_mul_f32_e32 v141, v141, v235
	v_mul_f32_e32 v142, v142, v235
	v_mul_f32_e32 v143, v143, v235
	v_fma_f32 v140, v140, v24, v40
	v_fma_f32 v141, v141, v25, v41
	v_fma_f32 v142, v142, v26, v42
	v_fma_f32 v143, v143, v27, v43
	v_cvt_pk_bf16_f32 v140, v140, v141
	v_cvt_pk_bf16_f32 v141, v142, v143
	global_store_dwordx2 v106, v[140:141], s[22:23] offset:1024
	v_mul_f32_e32 v144, v144, v235
	v_mul_f32_e32 v145, v145, v235
	v_mul_f32_e32 v146, v146, v235
	v_mul_f32_e32 v147, v147, v235
	v_fma_f32 v144, v144, v28, v44
	v_fma_f32 v145, v145, v29, v45
	v_fma_f32 v146, v146, v30, v46
	v_fma_f32 v147, v147, v31, v47
	v_cvt_pk_bf16_f32 v144, v144, v145
	v_cvt_pk_bf16_f32 v145, v146, v147
	global_store_dwordx2 v106, v[144:145], s[22:23] offset:1536
	s_add_i32 s18, s18, s14
	s_lshl_b32 s20, s18, 11
	s_add_u32 s22, s12, s20
	s_addc_u32 s23, s13, 0
	v_mul_f32_e32 v148, v148, v236
	v_mul_f32_e32 v149, v149, v236
	v_mul_f32_e32 v150, v150, v236
	v_mul_f32_e32 v151, v151, v236
	v_fma_f32 v148, v148, v16, v32
	v_fma_f32 v149, v149, v17, v33
	v_fma_f32 v150, v150, v18, v34
	v_fma_f32 v151, v151, v19, v35
	v_cvt_pk_bf16_f32 v148, v148, v149
	v_cvt_pk_bf16_f32 v149, v150, v151
	global_store_dwordx2 v106, v[148:149], s[22:23]
	v_mul_f32_e32 v152, v152, v236
	v_mul_f32_e32 v153, v153, v236
	v_mul_f32_e32 v154, v154, v236
	v_mul_f32_e32 v155, v155, v236
	v_fma_f32 v152, v152, v20, v36
	v_fma_f32 v153, v153, v21, v37
	v_fma_f32 v154, v154, v22, v38
	v_fma_f32 v155, v155, v23, v39
	v_cvt_pk_bf16_f32 v152, v152, v153
	v_cvt_pk_bf16_f32 v153, v154, v155
	global_store_dwordx2 v106, v[152:153], s[22:23] offset:512
	v_mul_f32_e32 v156, v156, v236
	v_mul_f32_e32 v157, v157, v236
	v_mul_f32_e32 v158, v158, v236
; __device__ __forceinline__ unsigned pk2(float lo, float hi) { f32x2_t v = {lo, hi}; bf16x2_t b = __builtin_convertvector(v, bf16x2_t); return __builtin_bit_cast(unsigned, b); }
; __device__ __forceinline__ void norm_mod_phase(const float* X, const float* ng, const float* mod, bf16* H, int G) {
;     ...
;             for (int r = 0; r < 4; ++r) { if (!has[r]) continue;
;                 const float rs = __builtin_amdgcn_rsqf(s[r] * (1.f / D) + EPSN); v2u* o8 = (v2u*)(H + (size_t)mr[r] * D) + lane;
; #pragma unroll
;                 for (int j = 0; j < 4; ++j) { const f32x4 h = v[r][j] * rs * gs[j] + sh[j]; o8[64 * j] = (v2u){pk2(h.x, h.y), pk2(h.z, h.w)}; } }
	v_mul_f32_e32 v159, v159, v236
	v_fma_f32 v156, v156, v24, v40
	v_fma_f32 v157, v157, v25, v41
	v_fma_f32 v158, v158, v26, v42
	v_fma_f32 v159, v159, v27, v43
	v_cvt_pk_bf16_f32 v156, v156, v157
	v_cvt_pk_bf16_f32 v157, v158, v159
	global_store_dwordx2 v106, v[156:157], s[22:23] offset:1024
	v_mul_f32_e32 v160, v160, v236
	v_mul_f32_e32 v161, v161, v236
	v_mul_f32_e32 v162, v162, v236
	v_mul_f32_e32 v163, v163, v236
	v_fma_f32 v160, v160, v28, v44
	v_fma_f32 v161, v161, v29, v45
	v_fma_f32 v162, v162, v30, v46
	v_fma_f32 v163, v163, v31, v47
	v_cvt_pk_bf16_f32 v160, v160, v161
	v_cvt_pk_bf16_f32 v161, v162, v163
	global_store_dwordx2 v106, v[160:161], s[22:23] offset:1536
	s_add_i32 s18, s18, s14
	s_lshl_b32 s20, s18, 11
	s_add_u32 s22, s12, s20
	s_addc_u32 s23, s13, 0
	v_mul_f32_e32 v164, v164, v237
	v_mul_f32_e32 v165, v165, v237
	v_mul_f32_e32 v166, v166, v237
	v_mul_f32_e32 v167, v167, v237
	v_fma_f32 v164, v164, v16, v32
	v_fma_f32 v165, v165, v17, v33
	v_fma_f32 v166, v166, v18, v34
	v_fma_f32 v167, v167, v19, v35
	v_cvt_pk_bf16_f32 v164, v164, v165
	v_cvt_pk_bf16_f32 v165, v166, v167
	global_store_dwordx2 v106, v[164:165], s[22:23]
	v_mul_f32_e32 v168, v168, v237
	v_mul_f32_e32 v169, v169, v237
	v_mul_f32_e32 v170, v170, v237
	v_mul_f32_e32 v171, v171, v237
	v_fma_f32 v168, v168, v20, v36
	v_fma_f32 v169, v169, v21, v37
	v_fma_f32 v170, v170, v22, v38
	v_fma_f32 v171, v171, v23, v39
	v_cvt_pk_bf16_f32 v168, v168, v169
	v_cvt_pk_bf16_f32 v169, v170, v171
	global_store_dwordx2 v106, v[168:169], s[22:23] offset:512
	v_mul_f32_e32 v172, v172, v237
	v_mul_f32_e32 v173, v173, v237
	v_mul_f32_e32 v174, v174, v237
	v_mul_f32_e32 v175, v175, v237
	v_fma_f32 v172, v172, v24, v40
	v_fma_f32 v173, v173, v25, v41
	v_fma_f32 v174, v174, v26, v42
	v_fma_f32 v175, v175, v27, v43
	v_cvt_pk_bf16_f32 v172, v172, v173
	v_cvt_pk_bf16_f32 v173, v174, v175
	global_store_dwordx2 v106, v[172:173], s[22:23] offset:1024
	v_mul_f32_e32 v176, v176, v237
	v_mul_f32_e32 v177, v177, v237
	v_mul_f32_e32 v178, v178, v237
	v_mul_f32_e32 v179, v179, v237
	v_fma_f32 v176, v176, v28, v44
	v_fma_f32 v177, v177, v29, v45
	v_fma_f32 v178, v178, v30, v46
	v_fma_f32 v179, v179, v31, v47
	v_cvt_pk_bf16_f32 v176, v176, v177
	v_cvt_pk_bf16_f32 v177, v178, v179
	global_store_dwordx2 v106, v[176:177], s[22:23] offset:1536
	s_add_i32 s18, s16, 8192
	s_lshl_b32 s20, s18, 11
	s_add_u32 s22, s12, s20
	s_addc_u32 s23, s13, 0
	v_mul_f32_e32 v180, v180, v238
	v_mul_f32_e32 v181, v181, v238
	v_mul_f32_e32 v182, v182, v238
	v_mul_f32_e32 v183, v183, v238
	v_fma_f32 v180, v180, v48, v64
	v_fma_f32 v181, v181, v49, v65
	v_fma_f32 v182, v182, v50, v66
	v_fma_f32 v183, v183, v51, v67
	v_cvt_pk_bf16_f32 v180, v180, v181
	v_cvt_pk_bf16_f32 v181, v182, v183
	global_store_dwordx2 v106, v[180:181], s[22:23]
	v_mul_f32_e32 v184, v184, v238
	v_mul_f32_e32 v185, v185, v238
	v_mul_f32_e32 v186, v186, v238
	v_mul_f32_e32 v187, v187, v238
	v_fma_f32 v184, v184, v52, v68
	v_fma_f32 v185, v185, v53, v69
	v_fma_f32 v186, v186, v54, v70
	v_fma_f32 v187, v187, v55, v71
	v_cvt_pk_bf16_f32 v184, v184, v185
	v_cvt_pk_bf16_f32 v185, v186, v187
	global_store_dwordx2 v106, v[184:185], s[22:23] offset:512
	v_mul_f32_e32 v188, v188, v238
	v_mul_f32_e32 v189, v189, v238
	v_mul_f32_e32 v190, v190, v238
	v_mul_f32_e32 v191, v191, v238
	v_fma_f32 v188, v188, v56, v72
	v_fma_f32 v189, v189, v57, v73
	v_fma_f32 v190, v190, v58, v74
	v_fma_f32 v191, v191, v59, v75
	v_cvt_pk_bf16_f32 v188, v188, v189
	v_cvt_pk_bf16_f32 v189, v190, v191
	global_store_dwordx2 v106, v[188:189], s[22:23] offset:1024
	v_mul_f32_e32 v192, v192, v238
	v_mul_f32_e32 v193, v193, v238
	v_mul_f32_e32 v194, v194, v238
	v_mul_f32_e32 v195, v195, v238
	v_fma_f32 v192, v192, v60, v76
	v_fma_f32 v193, v193, v61, v77
	v_fma_f32 v194, v194, v62, v78
	v_fma_f32 v195, v195, v63, v79
	v_cvt_pk_bf16_f32 v192, v192, v193
	v_cvt_pk_bf16_f32 v193, v194, v195
	global_store_dwordx2 v106, v[192:193], s[22:23] offset:1536
	s_add_i32 s18, s18, s14
	s_lshl_b32 s20, s18, 11
	s_add_u32 s22, s12, s20
	s_addc_u32 s23, s13, 0
	v_mul_f32_e32 v86, v86, v239
	v_mul_f32_e32 v87, v87, v239
	v_mul_f32_e32 v88, v88, v239
	v_mul_f32_e32 v89, v89, v239
	v_fma_f32 v86, v86, v48, v64
	v_fma_f32 v87, v87, v49, v65
	v_fma_f32 v88, v88, v50, v66
	v_fma_f32 v89, v89, v51, v67
	v_cvt_pk_bf16_f32 v86, v86, v87
	v_cvt_pk_bf16_f32 v87, v88, v89
	global_store_dwordx2 v106, v[86:87], s[22:23]
	v_mul_f32_e32 v90, v90, v239
; __device__ __forceinline__ unsigned pk2(float lo, float hi) { f32x2_t v = {lo, hi}; bf16x2_t b = __builtin_convertvector(v, bf16x2_t); return __builtin_bit_cast(unsigned, b); }
; __device__ __forceinline__ void norm_mod_phase(const float* X, const float* ng, const float* mod, bf16* H, int G) {
;     ...
;     for (int b = 0; b < 2; ++b) {
;     ...
;             for (int r = 0; r < 4; ++r) { if (!has[r]) continue;
;                 const float rs = __builtin_amdgcn_rsqf(s[r] * (1.f / D) + EPSN); v2u* o8 = (v2u*)(H + (size_t)mr[r] * D) + lane;
; #pragma unroll
;                 for (int j = 0; j < 4; ++j) { const f32x4 h = v[r][j] * rs * gs[j] + sh[j]; o8[64 * j] = (v2u){pk2(h.x, h.y), pk2(h.z, h.w)}; } }
	v_mul_f32_e32 v91, v91, v239
	v_mul_f32_e32 v92, v92, v239
	v_mul_f32_e32 v93, v93, v239
	v_fma_f32 v90, v90, v52, v68
	v_fma_f32 v91, v91, v53, v69
	v_fma_f32 v92, v92, v54, v70
	v_fma_f32 v93, v93, v55, v71
	v_cvt_pk_bf16_f32 v90, v90, v91
	v_cvt_pk_bf16_f32 v91, v92, v93
	global_store_dwordx2 v106, v[90:91], s[22:23] offset:512
	v_mul_f32_e32 v94, v94, v239
	v_mul_f32_e32 v95, v95, v239
	v_mul_f32_e32 v96, v96, v239
	v_mul_f32_e32 v97, v97, v239
	v_fma_f32 v94, v94, v56, v72
	v_fma_f32 v95, v95, v57, v73
	v_fma_f32 v96, v96, v58, v74
	v_fma_f32 v97, v97, v59, v75
	v_cvt_pk_bf16_f32 v94, v94, v95
	v_cvt_pk_bf16_f32 v95, v96, v97
	global_store_dwordx2 v106, v[94:95], s[22:23] offset:1024
	v_mul_f32_e32 v98, v98, v239
	v_mul_f32_e32 v99, v99, v239
	v_mul_f32_e32 v100, v100, v239
	v_mul_f32_e32 v101, v101, v239
	v_fma_f32 v98, v98, v60, v76
	v_fma_f32 v99, v99, v61, v77
	v_fma_f32 v100, v100, v62, v78
	v_fma_f32 v101, v101, v63, v79
	v_cvt_pk_bf16_f32 v98, v98, v99
	v_cvt_pk_bf16_f32 v99, v100, v101
	global_store_dwordx2 v106, v[98:99], s[22:23] offset:1536
	s_add_i32 s18, s18, s14
	s_lshl_b32 s20, s18, 11
	s_add_u32 s22, s12, s20
	s_addc_u32 s23, s13, 0
	v_mul_f32_e32 v218, v218, v240
	v_mul_f32_e32 v219, v219, v240
	v_mul_f32_e32 v220, v220, v240
	v_mul_f32_e32 v221, v221, v240
	v_fma_f32 v218, v218, v48, v64
	v_fma_f32 v219, v219, v49, v65
	v_fma_f32 v220, v220, v50, v66
	v_fma_f32 v221, v221, v51, v67
	v_cvt_pk_bf16_f32 v218, v218, v219
	v_cvt_pk_bf16_f32 v219, v220, v221
	global_store_dwordx2 v106, v[218:219], s[22:23]
	v_mul_f32_e32 v222, v222, v240
	v_mul_f32_e32 v223, v223, v240
	v_mul_f32_e32 v224, v224, v240
	v_mul_f32_e32 v225, v225, v240
	v_fma_f32 v222, v222, v52, v68
	v_fma_f32 v223, v223, v53, v69
	v_fma_f32 v224, v224, v54, v70
	v_fma_f32 v225, v225, v55, v71
	v_cvt_pk_bf16_f32 v222, v222, v223
	v_cvt_pk_bf16_f32 v223, v224, v225
	global_store_dwordx2 v106, v[222:223], s[22:23] offset:512
	v_mul_f32_e32 v226, v226, v240
	v_mul_f32_e32 v227, v227, v240
	v_mul_f32_e32 v228, v228, v240
	v_mul_f32_e32 v229, v229, v240
	v_fma_f32 v226, v226, v56, v72
	v_fma_f32 v227, v227, v57, v73
	v_fma_f32 v228, v228, v58, v74
	v_fma_f32 v229, v229, v59, v75
	v_cvt_pk_bf16_f32 v226, v226, v227
	v_cvt_pk_bf16_f32 v227, v228, v229
	global_store_dwordx2 v106, v[226:227], s[22:23] offset:1024
	v_mul_f32_e32 v230, v230, v240
	v_mul_f32_e32 v231, v231, v240
	v_mul_f32_e32 v232, v232, v240
	v_mul_f32_e32 v233, v233, v240
	v_fma_f32 v230, v230, v60, v76
	v_fma_f32 v231, v231, v61, v77
	v_fma_f32 v232, v232, v62, v78
	v_fma_f32 v233, v233, v63, v79
	v_cvt_pk_bf16_f32 v230, v230, v231
	v_cvt_pk_bf16_f32 v231, v232, v233
	global_store_dwordx2 v106, v[230:231], s[22:23] offset:1536
	s_add_i32 s18, s18, s14
	s_lshl_b32 s20, s18, 11
	s_add_u32 s22, s12, s20
	s_addc_u32 s23, s13, 0
	v_mul_f32_e32 v196, v196, v241
	v_mul_f32_e32 v197, v197, v241
	v_mul_f32_e32 v198, v198, v241
	v_mul_f32_e32 v199, v199, v241
	v_fma_f32 v196, v196, v48, v64
	v_fma_f32 v197, v197, v49, v65
	v_fma_f32 v198, v198, v50, v66
	v_fma_f32 v199, v199, v51, v67
	v_cvt_pk_bf16_f32 v196, v196, v197
	v_cvt_pk_bf16_f32 v197, v198, v199
	global_store_dwordx2 v106, v[196:197], s[22:23]
	v_mul_f32_e32 v200, v200, v241
	v_mul_f32_e32 v201, v201, v241
	v_mul_f32_e32 v202, v202, v241
	v_mul_f32_e32 v203, v203, v241
	v_fma_f32 v200, v200, v52, v68
	v_fma_f32 v201, v201, v53, v69
	v_fma_f32 v202, v202, v54, v70
	v_fma_f32 v203, v203, v55, v71
	v_cvt_pk_bf16_f32 v200, v200, v201
	v_cvt_pk_bf16_f32 v201, v202, v203
	global_store_dwordx2 v106, v[200:201], s[22:23] offset:512
	v_mul_f32_e32 v204, v204, v241
	v_mul_f32_e32 v205, v205, v241
	v_mul_f32_e32 v206, v206, v241
	v_mul_f32_e32 v207, v207, v241
	v_fma_f32 v204, v204, v56, v72
	v_fma_f32 v205, v205, v57, v73
	v_fma_f32 v206, v206, v58, v74
	v_fma_f32 v207, v207, v59, v75
	v_cvt_pk_bf16_f32 v204, v204, v205
	v_cvt_pk_bf16_f32 v205, v206, v207
	global_store_dwordx2 v106, v[204:205], s[22:23] offset:1024
	v_mul_f32_e32 v102, v102, v241
	v_mul_f32_e32 v103, v103, v241
	v_mul_f32_e32 v104, v104, v241
	v_mul_f32_e32 v105, v105, v241
	v_fma_f32 v102, v102, v60, v76
	v_fma_f32 v103, v103, v61, v77
	v_fma_f32 v104, v104, v62, v78
	v_fma_f32 v105, v105, v63, v79
	v_cvt_pk_bf16_f32 v102, v102, v103
	v_cvt_pk_bf16_f32 v103, v104, v105
	global_store_dwordx2 v106, v[102:103], s[22:23] offset:1536
	s_branch .LBB0_96
.Lnorm_orig:
	s_mov_b32 s16, 0
	s_branch .LBB0_87
